# attA loop-back pop: thread 0 no longer waits vmcnt(0) (which now only waited for the 4 output stores just issued; the prefetched pop already returned before the end of the epilogue); rest identical to
# baseline (speedup 1.0000x reference)
; __global__ void __launch_bounds__(NTHR, 2) fwd_kernel(Ptrs P) {
;     ...
;             for (;;) {
;                 if (tid == 0) *qslot = (int)atomicAdd((unsigned*)(ws + 256 + 256 * xq), 1u);
;                 __syncthreads();
;                 const int idx = *qslot;
.LBB0_384:
	s_and_b64 vcc, exec, s[2:3]
	s_cbranch_vccnz .LBB0_381
	s_and_saveexec_b64 s[2:3], s[8:9]
	s_cbranch_execz .LBB0_389
	v_mov_b32_e32 v0, 0
	s_branch .La_pop_ready

; __global__ void __launch_bounds__(NTHR, 2) fwd_kernel(Ptrs P) {
;     ...
;                 if (tid == 0) *qslot = (int)atomicAdd((unsigned*)(ws + 256 + 256 * xq), 1u);
;                 __syncthreads();
;                 const int idx = *qslot;
.La_pop_ready:
	v_readfirstlane_b32 s4, v241
	v_mov_b32_e32 v2, s50
	s_nop 0
	v_add_u32_e32 v0, s4, v0
	ds_write_b32 v2, v0
